# adds: gMLP spatial weights W[g] loaded/masked/converted once per workgroup and reused for its other SGU items
# baseline (speedup 1.0000x reference)
; __device__ __forceinline__ float bflo(unsigned w) { return __uint_as_float(w << 16); }
; __device__ __forceinline__ float bfhi(unsigned w) { return __uint_as_float(w & 0xffff0000u); }
; __device__ __forceinline__ void sgu_item(LAS unsigned char* lds, const bf16_t* z, const float* lng, const float* lnb, const float* wsg, const float* bsg, bf16_t* cat, int b, int c, int g) {
;     ...
;     const size_t row0 = (size_t)b * SEQ + c * 128;
;     const int p = tid >> 2, part = tid & 3;
;     const int t0 = wave * 16;
;     u32x4 vw[4], uw[4]; f32x4 w0[4], w1[4];
;     { const bf16_t* src = z + (row0 + p) * 5120 + 4096 + g * 128 + part * 32; const bf16_t* up = z + (row0 + p) * 5120 + 3072 + g * 128 + part * 32;
; #pragma unroll
;       for (int q = 0; q < 4; ++q) { vw[q] = *(const u32x4*)(src + q * 8); uw[q] = *(const u32x4*)(up + q * 8); }
;       const float* wp = wsg + ((size_t)g * 128 + t0 + lq) * 128 + quad * 8;
; #pragma unroll
;       for (int ks = 0; ks < 4; ++ks) { w0[ks] = *(const f32x4*)(wp + ks * 32); w1[ks] = *(const f32x4*)(wp + ks * 32 + 4); } }
;     {   float x[32];
; #pragma unroll
;         for (int q = 0; q < 4; ++q) { const u32x4 w = vw[q];
;             x[q * 8 + 0] = bflo(w.x); x[q * 8 + 1] = bfhi(w.x); x[q * 8 + 2] = bflo(w.y); x[q * 8 + 3] = bfhi(w.y); x[q * 8 + 4] = bflo(w.z); x[q * 8 + 5] = bfhi(w.z); x[q * 8 + 6] = bflo(w.w); x[q * 8 + 7] = bfhi(w.w); }
;         float s = 0.f;
; #pragma unroll
;         for (int d = 0; d < 32; ++d) s += x[d];
.LBB0_1668:
	s_mov_b64 s[2:3], s[0:1]
	s_load_dwordx2 s[2:3], s[2:3], 0x30
	s_ashr_i32 s18, s16, 7
	s_mov_b64 s[8:9], s[0:1]
	v_mov_b32_e32 v63, v226
	v_mov_b64_e32 v[0:1], s[92:93]
	s_waitcnt lgkmcnt(0)
	s_add_u32 s10, s2, s6
	s_addc_u32 s11, s3, s7
	s_mov_b64 s[2:3], s[0:1]
	s_load_dwordx2 s[2:3], s[2:3], 0x38
	v_mov_b32_e32 v21, v9
	s_waitcnt lgkmcnt(0)
	s_add_u32 s12, s2, s6
	s_addc_u32 s13, s3, s7
	s_mov_b64 s[2:3], s[0:1]
	s_load_dwordx2 s[2:3], s[2:3], 0x40
	s_load_dwordx2 s[8:9], s[8:9], 0x48
	s_waitcnt lgkmcnt(0)
	s_add_u32 s2, s2, s4
	s_addc_u32 s3, s3, s5
	s_ashr_i32 s19, s18, 31
	s_lshl_b64 s[20:21], s[18:19], 11
	s_and_b32 s18, s15, 0x780
	s_waitcnt vmcnt(9)
	v_ashrrev_i32_e32 v66, 2, v63
	s_or_b32 s20, s20, s18
	v_ashrrev_i32_e32 v67, 31, v66
	v_readfirstlane_b32 s17, v63
	v_lshl_add_u64 v[68:69], s[20:21], 0, v[66:67]
	s_ashr_i32 s19, s17, 2
	v_mad_u64_u32 v[0:1], s[20:21], v68, s77, v[0:1]
	s_and_b32 s17, s14, 0x380
	v_lshlrev_b32_e32 v2, 5, v63
	v_mad_i32_i24 v1, v69, s77, v1
	s_lshl_b32 s56, s17, 1
	v_and_b32_e32 v67, 0x60, v2
	v_lshlrev_b32_e32 v8, 1, v67
	v_lshl_add_u64 v[0:1], v[0:1], 0, s[56:57]
	v_lshl_add_u64 v[0:1], v[0:1], 0, v[8:9]
	s_movk_i32 s18, 0x2000
	v_add_co_u32_e32 v4, vcc, s18, v0
	s_mov_b64 s[20:21], 0x2000
	s_nop 0
	v_addc_co_u32_e32 v5, vcc, 0, v1, vcc
	v_lshl_add_u64 v[2:3], v[0:1], 0, s[20:21]
	global_load_dwordx4 v[54:57], v[4:5], off
	global_load_dwordx4 v[50:53], v[2:3], off offset:48
	global_load_dwordx4 v[94:97], v[2:3], off offset:32
	global_load_dwordx4 v[72:75], v[2:3], off offset:16
	s_mov_b64 s[20:21], 0x1800
	v_lshl_add_u64 v[10:11], v[0:1], 0, s[20:21]
	v_add_co_u32_e32 v0, vcc, s75, v0
	s_and_b32 s18, s19, -16
	s_nop 0
	v_addc_co_u32_e32 v1, vcc, 0, v1, vcc
	s_ashr_i32 s20, s18, 31
	s_add_u32 s21, s18, s17
	s_waitcnt vmcnt(12)
	v_and_b32_e32 v70, 15, v63
	s_addc_u32 s20, s20, 0
	v_or_b32_e32 v18, s21, v70
	v_mov_b32_e32 v19, s20
	v_bfe_u32 v71, v63, 4, 2
	v_lshlrev_b64 v[18:19], 9, v[18:19]
	v_lshl_add_u64 v[18:19], s[2:3], 0, v[18:19]
	v_lshlrev_b32_e32 v20, 5, v71
	v_lshl_add_u64 v[22:23], v[18:19], 0, v[20:21]
	global_load_dwordx4 v[14:17], v[0:1], off offset:2048
	s_nop 0
	global_load_dwordx4 v[0:3], v[10:11], off offset:48
	global_load_dwordx4 v[4:7], v[10:11], off offset:32
	s_nop 0
	global_load_dwordx4 v[10:13], v[10:11], off offset:16
	s_nop 0
	s_mov_b32 s3, 0
	s_and_b32 s2, s48, 7
	s_cbranch_scc1 .Lmy_w_do
	s_cmp_lg_u32 s16, s71
	s_cbranch_scc0 .Lmy_w_do
	s_mov_b32 s3, 1
	s_branch .Lmy_w_skip
.Lmy_w_do:
	global_load_dwordx4 v[46:49], v[22:23], off offset:16
	global_load_dwordx4 v[42:45], v[22:23], off
	global_load_dwordx4 v[34:37], v[22:23], off offset:144
	global_load_dwordx4 v[38:41], v[22:23], off offset:128
	global_load_dwordx4 v[26:29], v[22:23], off offset:272
	global_load_dwordx4 v[30:33], v[22:23], off offset:256
	global_load_dwordx4 v[18:21], v[22:23], off offset:400
	s_nop 0
	global_load_dwordx4 v[22:25], v[22:23], off offset:384
.Lmy_w_skip:
	v_or_b32_e32 v152, s17, v67
	v_lshlrev_b32_e32 v152, 2, v152
	global_load_dwordx2 v[120:121], v152, s[10:11]
	global_load_dwordx2 v[154:155], v152, s[12:13]
	global_load_dwordx2 v[122:123], v152, s[10:11] offset:8
	global_load_dwordx2 v[156:157], v152, s[12:13] offset:8
	global_load_dwordx2 v[124:125], v152, s[10:11] offset:16
	global_load_dwordx2 v[158:159], v152, s[12:13] offset:16
	global_load_dwordx2 v[126:127], v152, s[10:11] offset:24
	global_load_dwordx2 v[160:161], v152, s[12:13] offset:24
	global_load_dwordx2 v[128:129], v152, s[10:11] offset:32
	global_load_dwordx2 v[162:163], v152, s[12:13] offset:32
	global_load_dwordx2 v[130:131], v152, s[10:11] offset:40
	global_load_dwordx2 v[164:165], v152, s[12:13] offset:40
	global_load_dwordx2 v[132:133], v152, s[10:11] offset:48
	global_load_dwordx2 v[166:167], v152, s[12:13] offset:48
	global_load_dwordx2 v[134:135], v152, s[10:11] offset:56
	global_load_dwordx2 v[168:169], v152, s[12:13] offset:56
	global_load_dwordx2 v[136:137], v152, s[10:11] offset:64
	global_load_dwordx2 v[170:171], v152, s[12:13] offset:64
	global_load_dwordx2 v[138:139], v152, s[10:11] offset:72
	global_load_dwordx2 v[172:173], v152, s[12:13] offset:72
	global_load_dwordx2 v[140:141], v152, s[10:11] offset:80
	global_load_dwordx2 v[174:175], v152, s[12:13] offset:80
	global_load_dwordx2 v[142:143], v152, s[10:11] offset:88
	global_load_dwordx2 v[176:177], v152, s[12:13] offset:88
	global_load_dwordx2 v[144:145], v152, s[10:11] offset:96
	global_load_dwordx2 v[178:179], v152, s[12:13] offset:96
	global_load_dwordx2 v[146:147], v152, s[10:11] offset:104
	global_load_dwordx2 v[180:181], v152, s[12:13] offset:104
	global_load_dwordx2 v[148:149], v152, s[10:11] offset:112
	global_load_dwordx2 v[182:183], v152, s[12:13] offset:112
	global_load_dwordx2 v[150:151], v152, s[10:11] offset:120
	global_load_dwordx2 v[184:185], v152, s[12:13] offset:120
	v_lshlrev_b32_e32 v62, 3, v71
	s_movk_i32 s2, 0x110
	s_cmp_lt_i32 s19, 0
	s_waitcnt vmcnt(39)
	v_lshlrev_b32_e32 v58, 16, v54
	v_and_b32_e32 v92, 0xffff0000, v54
	v_add_f32_e32 v54, 0, v58
	v_lshlrev_b32_e32 v91, 16, v55
	v_add_f32_e32 v54, v54, v92
	v_and_b32_e32 v90, 0xffff0000, v55
	v_add_f32_e32 v54, v54, v91
	v_lshlrev_b32_e32 v89, 16, v56
	v_add_f32_e32 v54, v54, v90
	v_and_b32_e32 v88, 0xffff0000, v56
	v_add_f32_e32 v54, v54, v89
	v_lshlrev_b32_e32 v87, 16, v57
	v_add_f32_e32 v54, v54, v88
	v_and_b32_e32 v86, 0xffff0000, v57
	v_add_f32_e32 v54, v54, v87
	s_waitcnt vmcnt(36)
; __device__ __forceinline__ unsigned cvt_pk_bf16(float lo, float hi) { unsigned r; asm volatile("v_cvt_pk_bf16_f32 %0, %1, %2" : "=v"(r) : "v"(lo), "v"(hi)); return r; }
; __device__ __forceinline__ float bflo(unsigned w) { return __uint_as_float(w << 16); }
; __device__ __forceinline__ float bfhi(unsigned w) { return __uint_as_float(w & 0xffff0000u); }
; __device__ __forceinline__ void sgu_item(LAS unsigned char* lds, const bf16_t* z, const float* lng, const float* lnb, const float* wsg, const float* bsg, bf16_t* cat, int b, int c, int g) {
;     ...
;     {   float x[32];
; #pragma unroll
;         for (int q = 0; q < 4; ++q) { const u32x4 w = vw[q];
;             x[q * 8 + 0] = bflo(w.x); x[q * 8 + 1] = bfhi(w.x); x[q * 8 + 2] = bflo(w.y); x[q * 8 + 3] = bfhi(w.y); x[q * 8 + 4] = bflo(w.z); x[q * 8 + 5] = bfhi(w.z); x[q * 8 + 6] = bflo(w.w); x[q * 8 + 7] = bfhi(w.w); }
;         float s = 0.f;
; #pragma unroll
;         for (int d = 0; d < 32; ++d) s += x[d];
;         s += __shfl_xor(s, 1); s += __shfl_xor(s, 2);
;         const float mu = s * (1.0f / 128.0f); float q2 = 0.f;
; #pragma unroll
;         for (int d = 0; d < 32; ++d) { const float dd = x[d] - mu; q2 += dd * dd; }
;         q2 += __shfl_xor(q2, 1); q2 += __shfl_xor(q2, 2);
;         const float rstd = rsqrtf(q2 * (1.0f / 128.0f) + 1e-5f);
; #pragma unroll
;         for (int d = 0; d < 32; d += 2) { const int dc = g * 128 + part * 32 + d;
;             const float y0 = (x[d] - mu) * rstd * lng[dc] + lnb[dc], y1 = (x[d + 1] - mu) * rstd * lng[dc + 1] + lnb[dc + 1];
;             const unsigned w = cvt_pk_bf16(y0, y1);
;             vnT[(part * 32 + d) * 136 + p] = (bf16_t)(w & 0xffffu); vnT[(part * 32 + d + 1) * 136 + p] = (bf16_t)(w >> 16); }
	v_lshlrev_b32_e32 v85, 16, v72
	v_add_f32_e32 v54, v54, v86
	v_and_b32_e32 v84, 0xffff0000, v72
	v_add_f32_e32 v54, v54, v85
	v_lshlrev_b32_e32 v83, 16, v73
	v_add_f32_e32 v54, v54, v84
	v_and_b32_e32 v82, 0xffff0000, v73
	v_add_f32_e32 v54, v54, v83
	v_lshlrev_b32_e32 v81, 16, v74
	v_add_f32_e32 v54, v54, v82
	v_and_b32_e32 v80, 0xffff0000, v74
	v_add_f32_e32 v54, v54, v81
	v_lshlrev_b32_e32 v79, 16, v75
	v_add_f32_e32 v54, v54, v80
	v_and_b32_e32 v78, 0xffff0000, v75
	v_add_f32_e32 v54, v54, v79
	v_lshlrev_b32_e32 v77, 16, v94
	v_add_f32_e32 v54, v54, v78
	v_and_b32_e32 v76, 0xffff0000, v94
	v_add_f32_e32 v54, v54, v77
	v_lshlrev_b32_e32 v75, 16, v95
	v_add_f32_e32 v54, v54, v76
	v_and_b32_e32 v74, 0xffff0000, v95
	v_add_f32_e32 v54, v54, v75
	v_lshlrev_b32_e32 v73, 16, v96
	v_add_f32_e32 v54, v54, v74
	v_and_b32_e32 v56, 64, v233
	v_and_b32_e32 v72, 0xffff0000, v96
	v_add_f32_e32 v54, v54, v73
	v_xor_b32_e32 v55, 1, v233
	v_add_u32_e32 v56, 64, v56
	v_lshlrev_b32_e32 v65, 16, v97
	v_add_f32_e32 v54, v54, v72
	v_cmp_lt_i32_e32 vcc, v55, v56
	v_and_b32_e32 v64, 0xffff0000, v97
	v_add_f32_e32 v54, v54, v65
	v_cndmask_b32_e32 v55, v233, v55, vcc
	v_add_f32_e32 v54, v54, v64
	v_lshlrev_b32_e32 v59, 2, v55
	v_xor_b32_e32 v55, 2, v233
	v_lshlrev_b32_e32 v57, 16, v50
	v_cmp_lt_i32_e32 vcc, v55, v56
	v_and_b32_e32 v56, 0xffff0000, v50
	v_add_f32_e32 v50, v54, v57
	v_and_b32_e32 v60, 0xffff0000, v53
	v_lshlrev_b32_e32 v61, 16, v53
	v_lshlrev_b32_e32 v53, 16, v51
	v_add_f32_e32 v50, v50, v56
	v_and_b32_e32 v94, 0xffff0000, v52
	v_lshlrev_b32_e32 v95, 16, v52
	v_and_b32_e32 v52, 0xffff0000, v51
	v_add_f32_e32 v50, v50, v53
	v_add_f32_e32 v50, v50, v52
	v_add_f32_e32 v50, v50, v95
	v_add_f32_e32 v50, v50, v94
	v_add_f32_e32 v50, v50, v61
	v_add_f32_e32 v50, v50, v60
	ds_bpermute_b32 v51, v59, v50
	v_cndmask_b32_e32 v55, v233, v55, vcc
	v_lshlrev_b32_e32 v93, 2, v55
	s_waitcnt lgkmcnt(0)
	v_add_f32_e32 v50, v50, v51
	ds_bpermute_b32 v51, v93, v50
	s_waitcnt lgkmcnt(0)
	v_add_f32_e32 v51, v50, v51
	v_fmac_f32_e32 v92, 0xbc000000, v51
	v_fmac_f32_e32 v58, 0xbc000000, v51
	v_mul_f32_e32 v96, v92, v92
	v_fmac_f32_e32 v96, v58, v58
	v_fmac_f32_e32 v91, 0xbc000000, v51
	v_fmac_f32_e32 v96, v91, v91
	v_fmac_f32_e32 v90, 0xbc000000, v51
	v_fmac_f32_e32 v96, v90, v90
	v_fmac_f32_e32 v89, 0xbc000000, v51
	v_fmac_f32_e32 v96, v89, v89
	v_fmac_f32_e32 v88, 0xbc000000, v51
	v_fmac_f32_e32 v96, v88, v88
	v_fmac_f32_e32 v87, 0xbc000000, v51
	v_fmac_f32_e32 v96, v87, v87
	v_fmac_f32_e32 v86, 0xbc000000, v51
	v_fmac_f32_e32 v96, v86, v86
	v_fmac_f32_e32 v85, 0xbc000000, v51
	v_fmac_f32_e32 v96, v85, v85
	v_fmac_f32_e32 v84, 0xbc000000, v51
	v_fmac_f32_e32 v96, v84, v84
	v_fmac_f32_e32 v83, 0xbc000000, v51
	v_fmac_f32_e32 v96, v83, v83
	v_fmac_f32_e32 v82, 0xbc000000, v51
	v_fmac_f32_e32 v96, v82, v82
	v_fmac_f32_e32 v81, 0xbc000000, v51
	v_fmac_f32_e32 v96, v81, v81
	v_fmac_f32_e32 v80, 0xbc000000, v51
	v_fmac_f32_e32 v96, v80, v80
	v_fmac_f32_e32 v79, 0xbc000000, v51
	v_fmac_f32_e32 v96, v79, v79
	v_fmac_f32_e32 v78, 0xbc000000, v51
	v_fmac_f32_e32 v96, v78, v78
	v_fmac_f32_e32 v77, 0xbc000000, v51
	v_fmac_f32_e32 v96, v77, v77
	v_fmac_f32_e32 v76, 0xbc000000, v51
	v_fmac_f32_e32 v96, v76, v76
	v_fmac_f32_e32 v75, 0xbc000000, v51
	v_fmac_f32_e32 v96, v75, v75
	v_fmac_f32_e32 v74, 0xbc000000, v51
	v_fmac_f32_e32 v96, v74, v74
	v_fmac_f32_e32 v73, 0xbc000000, v51
	v_fmac_f32_e32 v96, v73, v73
	v_fmac_f32_e32 v72, 0xbc000000, v51
	v_mul_f32_e32 v50, 0x3c000000, v51
	v_fmac_f32_e32 v96, v72, v72
	v_fmac_f32_e32 v65, 0xbc000000, v51
	v_fmac_f32_e32 v96, v65, v65
	v_fmac_f32_e32 v64, 0xbc000000, v51
	v_pk_add_f32 v[56:57], v[56:57], v[50:51] op_sel_hi:[1,0] neg_lo:[0,1] neg_hi:[0,1]
	v_fmac_f32_e32 v96, v64, v64
	v_pk_mul_f32 v[54:55], v[56:57], v[56:57]
	s_nop 0
	v_add_f32_e32 v51, v55, v96
	v_add_f32_e32 v51, v54, v51
	v_pk_add_f32 v[54:55], v[52:53], v[50:51] op_sel_hi:[1,0] neg_lo:[0,1] neg_hi:[0,1]
	s_nop 0
	v_pk_mul_f32 v[52:53], v[54:55], v[54:55]
	s_nop 0
	v_add_f32_e32 v51, v53, v51
	v_add_f32_e32 v51, v52, v51
	v_pk_add_f32 v[52:53], v[94:95], v[50:51] op_sel_hi:[1,0] neg_lo:[0,1] neg_hi:[0,1]
	s_nop 0
	v_pk_mul_f32 v[94:95], v[52:53], v[52:53]
	s_nop 0
	v_add_f32_e32 v51, v95, v51
	v_add_f32_e32 v94, v94, v51
	v_pk_add_f32 v[50:51], v[60:61], v[50:51] op_sel_hi:[1,0] neg_lo:[0,1] neg_hi:[0,1]
	s_nop 0
	v_pk_mul_f32 v[60:61], v[50:51], v[50:51]
	s_nop 0
	v_add_f32_e32 v61, v61, v94
	v_add_f32_e32 v60, v60, v61
	ds_bpermute_b32 v59, v59, v60
	s_waitcnt lgkmcnt(0)
	v_add_f32_e32 v59, v60, v59
	ds_bpermute_b32 v60, v93, v59
	s_waitcnt lgkmcnt(0)
	v_add_f32_e32 v59, v59, v60
	v_mov_b32_e32 v60, 0x3727c5ac
	v_fmamk_f32 v59, v59, 0x3c000000, v60
	v_cmp_gt_f32_e32 vcc, s33, v59
	v_mul_f32_e32 v60, 0x4b800000, v59
	s_nop 0
	v_cndmask_b32_e32 v59, v59, v60, vcc
	v_rsq_f32_e32 v59, v59
	s_nop 0
	v_mul_f32_e32 v60, 0x45800000, v59
	v_cndmask_b32_e32 v93, v59, v60, vcc
	v_or_b32_e32 v59, s17, v67
	v_lshlrev_b32_e32 v94, 2, v59
	v_mul_f32_e32 v95, v58, v93
	v_mul_f32_e32 v57, v57, v93
	v_mul_f32_e32 v56, v56, v93
	v_mul_f32_e32 v55, v55, v93
	v_mul_f32_e32 v54, v54, v93
	v_mul_f32_e32 v53, v53, v93
	v_mul_f32_e32 v52, v52, v93
	v_mul_f32_e32 v51, v51, v93
	v_mul_f32_e32 v50, v50, v93
	s_waitcnt vmcnt(30)
	v_fma_f32 v58, v120, v95, v154
	v_mul_f32_e32 v60, v92, v93
	v_fmac_f32_e32 v155, v121, v60
	v_cvt_pk_bf16_f32 v59, v58, v155
	v_mul_u32_u24_e32 v58, 0x110, v67
	v_lshlrev_b32_e32 v60, 1, v66
	v_add3_u32 v58, 0, v58, v60
	ds_write_b16 v58, v59
	ds_write_b16_d16_hi v58, v59 offset:272
	v_mul_f32_e32 v59, v91, v93
	s_waitcnt vmcnt(28)
; __device__ __forceinline__ unsigned cvt_pk_bf16(float lo, float hi) { unsigned r; asm volatile("v_cvt_pk_bf16_f32 %0, %1, %2" : "=v"(r) : "v"(lo), "v"(hi)); return r; }
; __device__ __forceinline__ void sgu_item(LAS unsigned char* lds, const bf16_t* z, const float* lng, const float* lnb, const float* wsg, const float* bsg, bf16_t* cat, int b, int c, int g) {
;     ...
; #pragma unroll
;         for (int d = 0; d < 32; d += 2) { const int dc = g * 128 + part * 32 + d;
;             const float y0 = (x[d] - mu) * rstd * lng[dc] + lnb[dc], y1 = (x[d + 1] - mu) * rstd * lng[dc + 1] + lnb[dc + 1];
;             const unsigned w = cvt_pk_bf16(y0, y1);
;             vnT[(part * 32 + d) * 136 + p] = (bf16_t)(w & 0xffffu); vnT[(part * 32 + d + 1) * 136 + p] = (bf16_t)(w >> 16); }
;     }
;     bf16x8 Aw[4];
;     {   const int t = t0 + lq;
; #pragma unroll
;         for (int ks = 0; ks < 4; ++ks) { const int sidx = ks * 32 + quad * 8;
; #pragma unroll
;             for (int e = 0; e < 4; ++e) { if (sidx + e > t) w0[ks][e] = 0.f; if (sidx + 4 + e > t) w1[ks][e] = 0.f; }
;             Aw[ks] = __builtin_bit_cast(bf16x8, pack8(w0[ks], w1[ks])); } }
	v_fma_f32 v59, v122, v59, v156
	v_mul_f32_e32 v60, v90, v93
	v_fmac_f32_e32 v157, v123, v60
	v_cvt_pk_bf16_f32 v59, v59, v157
	ds_write_b16 v58, v59 offset:544
	ds_write_b16_d16_hi v58, v59 offset:816
	v_mul_f32_e32 v59, v89, v93
	s_waitcnt vmcnt(26)
	v_fma_f32 v59, v124, v59, v158
	v_mul_f32_e32 v60, v88, v93
	v_fmac_f32_e32 v159, v125, v60
	v_cvt_pk_bf16_f32 v59, v59, v159
	ds_write_b16 v58, v59 offset:1088
	ds_write_b16_d16_hi v58, v59 offset:1360
	v_mul_f32_e32 v59, v87, v93
	s_waitcnt vmcnt(24)
	v_fma_f32 v59, v126, v59, v160
	v_mul_f32_e32 v60, v86, v93
	v_fmac_f32_e32 v161, v127, v60
	v_cvt_pk_bf16_f32 v59, v59, v161
	ds_write_b16 v58, v59 offset:1632
	ds_write_b16_d16_hi v58, v59 offset:1904
	v_mul_f32_e32 v59, v85, v93
	s_waitcnt vmcnt(22)
	v_fma_f32 v59, v128, v59, v162
	v_mul_f32_e32 v60, v84, v93
	v_fmac_f32_e32 v163, v129, v60
	v_cvt_pk_bf16_f32 v59, v59, v163
	ds_write_b16 v58, v59 offset:2176
	ds_write_b16_d16_hi v58, v59 offset:2448
	v_mul_f32_e32 v59, v83, v93
	s_waitcnt vmcnt(20)
	v_fma_f32 v59, v130, v59, v164
	v_mul_f32_e32 v60, v82, v93
	v_fmac_f32_e32 v165, v131, v60
	v_cvt_pk_bf16_f32 v59, v59, v165
	ds_write_b16 v58, v59 offset:2720
	ds_write_b16_d16_hi v58, v59 offset:2992
	v_mul_f32_e32 v59, v81, v93
	s_waitcnt vmcnt(18)
	v_fma_f32 v59, v132, v59, v166
	v_mul_f32_e32 v60, v80, v93
	v_fmac_f32_e32 v167, v133, v60
	v_cvt_pk_bf16_f32 v59, v59, v167
	ds_write_b16 v58, v59 offset:3264
	ds_write_b16_d16_hi v58, v59 offset:3536
	v_mul_f32_e32 v59, v79, v93
	s_waitcnt vmcnt(16)
	v_fma_f32 v59, v134, v59, v168
	v_mul_f32_e32 v60, v78, v93
	v_fmac_f32_e32 v169, v135, v60
	v_cvt_pk_bf16_f32 v59, v59, v169
	ds_write_b16 v58, v59 offset:3808
	ds_write_b16_d16_hi v58, v59 offset:4080
	v_mul_f32_e32 v59, v77, v93
	s_waitcnt vmcnt(14)
	v_fma_f32 v59, v136, v59, v170
	v_mul_f32_e32 v60, v76, v93
	v_fmac_f32_e32 v171, v137, v60
	v_cvt_pk_bf16_f32 v59, v59, v171
	ds_write_b16 v58, v59 offset:4352
	ds_write_b16_d16_hi v58, v59 offset:4624
	v_mul_f32_e32 v59, v75, v93
	s_waitcnt vmcnt(12)
	v_fma_f32 v59, v59, v138, v172
	v_mul_f32_e32 v60, v74, v93
	v_fmac_f32_e32 v173, v60, v139
	v_cvt_pk_bf16_f32 v59, v59, v173
	ds_write_b16 v58, v59 offset:4896
	ds_write_b16_d16_hi v58, v59 offset:5168
	v_mul_f32_e32 v59, v73, v93
	s_waitcnt vmcnt(10)
	v_fma_f32 v59, v59, v140, v174
	v_mul_f32_e32 v60, v72, v93
	v_fmac_f32_e32 v175, v60, v141
	v_cvt_pk_bf16_f32 v59, v59, v175
	ds_write_b16 v58, v59 offset:5440
	ds_write_b16_d16_hi v58, v59 offset:5712
	v_mul_f32_e32 v59, v65, v93
	s_waitcnt vmcnt(8)
	v_fma_f32 v59, v59, v142, v176
	v_mul_f32_e32 v60, v64, v93
	v_fmac_f32_e32 v177, v60, v143
	v_cvt_pk_bf16_f32 v59, v59, v177
	ds_write_b16 v58, v59 offset:5984
	ds_write_b16_d16_hi v58, v59 offset:6256
	s_waitcnt vmcnt(6)
	v_fma_f32 v57, v57, v144, v178
	v_fmac_f32_e32 v179, v56, v145
	v_cvt_pk_bf16_f32 v56, v57, v179
	ds_write_b16 v58, v56 offset:6528
	ds_write_b16_d16_hi v58, v56 offset:6800
	s_waitcnt vmcnt(4)
	v_fma_f32 v55, v55, v146, v180
	v_fmac_f32_e32 v181, v54, v147
	v_cvt_pk_bf16_f32 v54, v55, v181
	ds_write_b16 v58, v54 offset:7072
	ds_write_b16_d16_hi v58, v54 offset:7344
	s_waitcnt vmcnt(2)
	v_fma_f32 v53, v53, v148, v182
	v_fmac_f32_e32 v183, v52, v149
	v_cvt_pk_bf16_f32 v52, v53, v183
	ds_write_b16 v58, v52 offset:7616
	ds_write_b16_d16_hi v58, v52 offset:7888
	s_waitcnt vmcnt(0)
	v_fma_f32 v51, v51, v150, v184
	v_fmac_f32_e32 v185, v50, v151
	v_cvt_pk_bf16_f32 v50, v51, v185
	ds_write_b16 v58, v50 offset:8160
	ds_write_b16_d16_hi v58, v50 offset:8432
	s_cmp_lg_u32 s3, 0
	s_cbranch_scc1 .Lmy_aw_reuse
; #define LAS __attribute__((address_space(3)))
; __device__ __forceinline__ void sgu_item(LAS unsigned char* lds, const bf16_t* z, const float* lng, const float* lnb, const float* wsg, const float* bsg, bf16_t* cat, int b, int c, int g) {
;     ...
;     bf16x8 Aw[4];
;     {   const int t = t0 + lq;
; #pragma unroll
;         for (int ks = 0; ks < 4; ++ks) { const int sidx = ks * 32 + quad * 8;
; #pragma unroll
;             for (int e = 0; e < 4; ++e) { if (sidx + e > t) w0[ks][e] = 0.f; if (sidx + 4 + e > t) w1[ks][e] = 0.f; }
;             Aw[ks] = __builtin_bit_cast(bf16x8, pack8(w0[ks], w1[ks])); } }
;     __syncthreads();
;     f32x4 acc[8];
; #pragma unroll
;     for (int nt = 0; nt < 8; ++nt) acc[nt] = (f32x4){0.f, 0.f, 0.f, 0.f};
; #pragma unroll
;     for (int ks = 0; ks < 4; ++ks) {
;         const int s0 = ks * 32;
;         if (s0 <= t0 + 15) {
; #pragma unroll
;             for (int nt = 0; nt < 8; ++nt) { const bf16x8 Bv = *(const LAS bf16x8*)(vnT + (nt * 16 + lq) * 136 + s0 + quad * 8);
;                 acc[nt] = __builtin_amdgcn_mfma_f32_16x16x32_bf16(Aw[ks], Bv, acc[nt], 0, 0, 0); }
	v_bfi_b32 v50, -16, s19, v63
	v_cmp_gt_i32_e32 vcc, v62, v50
	v_mov_b32_e32 v52, s57
	s_nop 0
	v_cndmask_b32_e32 v54, v42, v52, vcc
	v_or_b32_e32 v52, 4, v62
	v_cndmask_b32_e32 v51, v44, v44, vcc
	v_cndmask_b32_e32 v53, v45, v45, vcc
	v_cmp_gt_i32_e32 vcc, v52, v50
	v_mov_b32_e32 v52, s57
	s_nop 0
	v_cndmask_b32_e32 v46, v46, v52, vcc
	v_cndmask_b32_e32 v49, v49, v49, vcc
	v_cndmask_b32_e32 v48, v48, v48, vcc
	v_cndmask_b32_e32 v47, v47, v47, vcc
	v_cmp_lt_i32_e32 vcc, v62, v50
	s_nop 1
	v_cndmask_b32_e32 v44, v51, v44, vcc
	v_or_b32_e32 v51, 5, v62
	v_cndmask_b32_e32 v42, v54, v42, vcc
	v_cndmask_b32_e32 v45, v53, v45, vcc
	v_cndmask_b32_e32 v43, 0, v43, vcc
	v_cmp_le_i32_e32 vcc, v51, v50
	v_or_b32_e32 v51, 2, v62
	v_cvt_pk_bf16_f32 v42, v42, v43
	s_nop 0
	v_cndmask_b32_e32 v47, 0, v47, vcc
	v_cmp_le_i32_e32 vcc, v51, v50
	v_or_b32_e32 v51, 6, v62
	s_nop 0
	v_cndmask_b32_e32 v44, 0, v44, vcc
	v_cmp_le_i32_e32 vcc, v51, v50
	v_or_b32_e32 v51, 3, v62
	s_nop 0
	v_cndmask_b32_e32 v48, 0, v48, vcc
	v_cmp_le_i32_e32 vcc, v51, v50
	v_or_b32_e32 v51, 7, v62
	s_nop 0
	v_cndmask_b32_e32 v45, 0, v45, vcc
	v_cmp_le_i32_e32 vcc, v51, v50
	v_cvt_pk_bf16_f32 v43, v44, v45
	v_cvt_pk_bf16_f32 v44, v46, v47
	v_or_b32_e32 v46, 32, v62
	s_nop 0
	v_cndmask_b32_e32 v49, 0, v49, vcc
	v_cmp_gt_i32_e32 vcc, v46, v50
	v_mov_b32_e32 v46, s57
	v_cvt_pk_bf16_f32 v45, v48, v49
	s_nop 0
	v_cndmask_b32_e32 v46, v38, v46, vcc
	v_or_b32_e32 v38, 36, v62
	v_cndmask_b32_e32 v41, v41, v41, vcc
	v_cndmask_b32_e32 v40, v40, v40, vcc
	v_cndmask_b32_e32 v39, v39, v39, vcc
	v_cmp_gt_i32_e32 vcc, v38, v50
	v_mov_b32_e32 v38, s57
	s_nop 0
	v_cndmask_b32_e32 v38, v34, v38, vcc
	v_cndmask_b32_e32 v34, v37, v37, vcc
	v_or_b32_e32 v37, 33, v62
	v_cndmask_b32_e32 v36, v36, v36, vcc
	v_cndmask_b32_e32 v35, v35, v35, vcc
	v_cmp_le_i32_e32 vcc, v37, v50
	s_nop 1
	v_cndmask_b32_e32 v37, 0, v39, vcc
	v_or_b32_e32 v39, 37, v62
	v_cmp_le_i32_e32 vcc, v39, v50
	s_nop 1
	v_cndmask_b32_e32 v39, 0, v35, vcc
	v_or_b32_e32 v35, 34, v62
	v_cmp_le_i32_e32 vcc, v35, v50
	s_nop 1
	v_cndmask_b32_e32 v35, 0, v40, vcc
	v_or_b32_e32 v40, 38, v62
	v_cmp_le_i32_e32 vcc, v40, v50
	s_nop 1
	v_cndmask_b32_e32 v40, 0, v36, vcc
	v_or_b32_e32 v36, 35, v62
	v_cmp_le_i32_e32 vcc, v36, v50
	s_nop 1
	v_cndmask_b32_e32 v36, 0, v41, vcc
	v_or_b32_e32 v41, 39, v62
	v_cmp_le_i32_e32 vcc, v41, v50
	s_nop 1
	v_cndmask_b32_e32 v41, 0, v34, vcc
	v_cvt_pk_bf16_f32 v34, v46, v37
	v_cvt_pk_bf16_f32 v35, v35, v36
	v_cvt_pk_bf16_f32 v36, v38, v39
	v_or_b32_e32 v38, 64, v62
	v_cmp_gt_i32_e32 vcc, v38, v50
	v_mov_b32_e32 v38, s57
	v_cvt_pk_bf16_f32 v37, v40, v41
	s_nop 0
	v_cndmask_b32_e32 v38, v30, v38, vcc
	v_or_b32_e32 v30, 0x44, v62
	v_cndmask_b32_e32 v33, v33, v33, vcc
	v_cndmask_b32_e32 v32, v32, v32, vcc
	v_cndmask_b32_e32 v31, v31, v31, vcc
	v_cmp_gt_i32_e32 vcc, v30, v50
	v_mov_b32_e32 v30, s57
	s_nop 0
	v_cndmask_b32_e32 v30, v26, v30, vcc
	v_cndmask_b32_e32 v26, v29, v29, vcc
	v_or_b32_e32 v29, 0x41, v62
	v_cndmask_b32_e32 v28, v28, v28, vcc
	v_cndmask_b32_e32 v27, v27, v27, vcc
	v_cmp_le_i32_e32 vcc, v29, v50
	s_nop 1
	v_cndmask_b32_e32 v29, 0, v31, vcc
	v_or_b32_e32 v31, 0x45, v62
	v_cmp_le_i32_e32 vcc, v31, v50
	s_nop 1
	v_cndmask_b32_e32 v31, 0, v27, vcc
	v_or_b32_e32 v27, 0x42, v62
	v_cmp_le_i32_e32 vcc, v27, v50
	s_nop 1
	v_cndmask_b32_e32 v27, 0, v32, vcc
	v_or_b32_e32 v32, 0x46, v62
	v_cmp_le_i32_e32 vcc, v32, v50
	s_nop 1
	v_cndmask_b32_e32 v32, 0, v28, vcc
	v_or_b32_e32 v28, 0x43, v62
	v_cmp_le_i32_e32 vcc, v28, v50
	s_nop 1
	v_cndmask_b32_e32 v28, 0, v33, vcc
	v_or_b32_e32 v33, 0x47, v62
	v_cmp_le_i32_e32 vcc, v33, v50
	s_nop 1
	v_cndmask_b32_e32 v33, 0, v26, vcc
	v_cvt_pk_bf16_f32 v26, v38, v29
	v_cvt_pk_bf16_f32 v27, v27, v28
	v_cvt_pk_bf16_f32 v28, v30, v31
	v_or_b32_e32 v30, 0x60, v62
	v_cmp_gt_i32_e32 vcc, v30, v50
	v_mov_b32_e32 v30, s57
	v_cvt_pk_bf16_f32 v29, v32, v33
	s_nop 0
	v_cndmask_b32_e32 v30, v22, v30, vcc
	v_or_b32_e32 v22, 0x64, v62
	v_cndmask_b32_e32 v25, v25, v25, vcc
	v_cndmask_b32_e32 v24, v24, v24, vcc
	v_cndmask_b32_e32 v23, v23, v23, vcc
	v_cmp_gt_i32_e32 vcc, v22, v50
	v_mov_b32_e32 v22, s57
	s_nop 0
	v_cndmask_b32_e32 v22, v18, v22, vcc
	v_cndmask_b32_e32 v18, v21, v21, vcc
	v_or_b32_e32 v21, 0x61, v62
	v_cndmask_b32_e32 v20, v20, v20, vcc
	v_cndmask_b32_e32 v19, v19, v19, vcc
	v_cmp_le_i32_e32 vcc, v21, v50
	s_nop 1
	v_cndmask_b32_e32 v21, 0, v23, vcc
	v_or_b32_e32 v23, 0x65, v62
	v_cmp_le_i32_e32 vcc, v23, v50
	s_nop 1
	v_cndmask_b32_e32 v23, 0, v19, vcc
	v_or_b32_e32 v19, 0x62, v62
	v_cmp_le_i32_e32 vcc, v19, v50
	s_nop 1
	v_cndmask_b32_e32 v19, 0, v24, vcc
	v_or_b32_e32 v24, 0x66, v62
	v_cmp_le_i32_e32 vcc, v24, v50
	s_nop 1
	v_cndmask_b32_e32 v24, 0, v20, vcc
	v_or_b32_e32 v20, 0x63, v62
	v_cmp_le_i32_e32 vcc, v20, v50
	s_nop 1
	v_cndmask_b32_e32 v20, 0, v25, vcc
	v_or_b32_e32 v25, 0x67, v62
	v_cmp_le_i32_e32 vcc, v25, v50
	s_nop 1
	v_cndmask_b32_e32 v25, 0, v18, vcc
	v_cvt_pk_bf16_f32 v18, v30, v21
	v_cvt_pk_bf16_f32 v19, v19, v20
	v_cvt_pk_bf16_f32 v20, v22, v23
	v_lshl_add_u32 v22, v71, 4, 0
	v_mad_u32_u24 v72, v70, s2, v22
	v_cvt_pk_bf16_f32 v21, v24, v25
	s_nop 0
	v_mov_b64_e32 v[206:207], v[18:19]
	v_mov_b64_e32 v[208:209], v[20:21]
	v_mov_b64_e32 v[210:211], v[26:27]
	v_mov_b64_e32 v[212:213], v[28:29]
	v_mov_b64_e32 v[214:215], v[34:35]
	v_mov_b64_e32 v[216:217], v[36:37]
	v_mov_b64_e32 v[218:219], v[42:43]
	v_mov_b64_e32 v[220:221], v[44:45]
	s_branch .Lmy_aw_join
.Lmy_aw_reuse:
	v_mov_b64_e32 v[18:19], v[206:207]
	v_mov_b64_e32 v[20:21], v[208:209]
	v_mov_b64_e32 v[26:27], v[210:211]
	v_mov_b64_e32 v[28:29], v[212:213]
	v_mov_b64_e32 v[34:35], v[214:215]
	v_mov_b64_e32 v[36:37], v[216:217]
	v_mov_b64_e32 v[42:43], v[218:219]
	v_mov_b64_e32 v[44:45], v[220:221]
	v_lshl_add_u32 v22, v71, 4, 0
	v_mad_u32_u24 v72, v70, s2, v22
.Lmy_aw_join:
	s_cmp_lt_i32 s19, 0
	s_waitcnt lgkmcnt(0)
	s_barrier
	s_cbranch_scc1 .LBB0_1670
	ds_read_b128 v[22:25], v72
	ds_read_b128 v[38:41], v72 offset:4352
	s_waitcnt lgkmcnt(1)
	v_mfma_f32_16x16x32_bf16 v[30:33], v[42:45], v[22:25], 0
	s_waitcnt lgkmcnt(0)
	v_mfma_f32_16x16x32_bf16 v[22:25], v[42:45], v[38:41], 0
	ds_read_b128 v[38:41], v72 offset:8704
	ds_read_b128 v[46:49], v72 offset:13056
	s_waitcnt lgkmcnt(1)
	v_mfma_f32_16x16x32_bf16 v[50:53], v[42:45], v[38:41], 0
	ds_read_b128 v[38:41], v72 offset:17408
	ds_read_b128 v[54:57], v72 offset:21760
	s_waitcnt lgkmcnt(1)
	v_mfma_f32_16x16x32_bf16 v[58:61], v[42:45], v[38:41], 0
	ds_read_b128 v[38:41], v72 offset:26112
	ds_read_b128 v[74:77], v72 offset:30464
	v_mfma_f32_16x16x32_bf16 v[46:49], v[42:45], v[46:49], 0
	s_waitcnt lgkmcnt(2)
	v_mfma_f32_16x16x32_bf16 v[54:57], v[42:45], v[54:57], 0
	s_waitcnt lgkmcnt(1)
	v_mfma_f32_16x16x32_bf16 v[62:65], v[42:45], v[38:41], 0
	s_waitcnt lgkmcnt(0)
	v_mfma_f32_16x16x32_bf16 v[38:41], v[42:45], v[74:77], 0
	s_or_b32 s2, s19, 15
	s_cmp_lt_i32 s2, 32
	s_cbranch_scc0 .LBB0_1671
	s_branch .LBB0_1672
